# P5 step B: fragment-ring waits exact per slice index (counted vmcnt instead of draining younger fetches)
# speedup vs baseline: 1.0026x; 1.0026x over previous
.LBB0_460:
	v_add_u32_e32 v162, 0, v162
	v_mad_u32_u24 v138, v169, s70, v162
	ds_read_b128 v[150:153], v138 offset:16384
	ds_read_b128 v[154:157], v138 offset:24832
	ds_read_b128 v[158:161], v138 offset:33280
	ds_read_b128 v[172:175], v138 offset:41728
	s_cmp_lg_u32 s75, 0
	s_cbranch_scc1 .Lw5_6_0
	s_waitcnt vmcnt(4) lgkmcnt(3)
	s_branch .Lw5_6_z
.Lw5_6_0:
	s_waitcnt vmcnt(12) lgkmcnt(3)
.Lw5_6_z:
	v_mfma_f32_16x16x32_bf16 v[2:5], v[134:137], v[150:153], v[2:5]
	s_waitcnt lgkmcnt(2)
	v_mfma_f32_16x16x32_bf16 v[6:9], v[134:137], v[154:157], v[6:9]
	s_waitcnt lgkmcnt(1)
	v_mfma_f32_16x16x32_bf16 v[10:13], v[134:137], v[158:161], v[10:13]
	s_waitcnt lgkmcnt(0)
	v_mfma_f32_16x16x32_bf16 v[14:17], v[134:137], v[172:175], v[14:17]
	v_mfma_f32_16x16x32_bf16 v[26:29], v[130:133], v[150:153], v[26:29]
	v_mfma_f32_16x16x32_bf16 v[30:33], v[130:133], v[154:157], v[30:33]
	v_mfma_f32_16x16x32_bf16 v[34:37], v[130:133], v[158:161], v[34:37]
	v_mfma_f32_16x16x32_bf16 v[138:141], v[130:133], v[172:175], v[38:41]
	v_mfma_f32_16x16x32_bf16 v[42:45], v[126:129], v[150:153], v[42:45]
	v_mfma_f32_16x16x32_bf16 v[46:49], v[126:129], v[154:157], v[46:49]
	v_mfma_f32_16x16x32_bf16 v[142:145], v[126:129], v[158:161], v[66:69]
	v_mfma_f32_16x16x32_bf16 v[146:149], v[126:129], v[172:175], v[86:89]
	v_mfma_f32_16x16x32_bf16 v[90:93], v[122:125], v[150:153], v[90:93]
	v_mfma_f32_16x16x32_bf16 v[150:153], v[122:125], v[154:157], v[94:97]
	v_mfma_f32_16x16x32_bf16 v[154:157], v[122:125], v[158:161], v[98:101]
	v_mfma_f32_16x16x32_bf16 v[158:161], v[122:125], v[172:175], v[102:105]
	v_cndmask_b32_e64 v38, 0, 1, s[38:39]
	v_cmp_ne_u32_e64 s[8:9], 1, v38
	s_andn2_b64 vcc, exec, s[38:39]
	s_cbranch_vccnz .LBB0_462
	v_add_co_u32_e32 v38, vcc, 0x80000, v166
	s_nop 1
	v_addc_co_u32_e32 v39, vcc, 0, v167, vcc
	global_load_dwordx4 v[134:137], v[38:39], off
	global_load_dwordx4 v[130:133], v[38:39], off offset:1024
	global_load_dwordx4 v[126:129], v[38:39], off offset:2048
	global_load_dwordx4 v[122:125], v[38:39], off offset:3072
.LBB0_462:
	v_mul_u32_u24_e32 v38, 0x210, v169
	v_add_u32_e32 v162, v162, v38
	ds_read_b128 v[172:175], v162 offset:16448
	ds_read_b128 v[176:179], v162 offset:33344
	ds_read_b128 v[180:183], v162 offset:41792
	s_cmp_lg_u32 s75, 0
	s_cbranch_scc1 .Lw5_5_0
	s_waitcnt vmcnt(0) lgkmcnt(2)
	s_branch .Lw5_5_z
.Lw5_5_0:
	s_cmp_lg_u32 s75, 1
	s_cbranch_scc1 .Lw5_5_1
	s_waitcnt vmcnt(8) lgkmcnt(2)
	s_branch .Lw5_5_z
.Lw5_5_1:
	s_waitcnt vmcnt(12) lgkmcnt(2)
.Lw5_5_z:
	v_mfma_f32_16x16x32_bf16 v[102:105], v[118:121], v[172:175], v[2:5]
	s_nop 2
	ds_read_b128 v[2:5], v162 offset:24896
	s_waitcnt lgkmcnt(2)
	v_mfma_f32_16x16x32_bf16 v[38:41], v[118:121], v[176:179], v[10:13]
	s_waitcnt lgkmcnt(0)
	v_mfma_f32_16x16x32_bf16 v[86:89], v[118:121], v[2:5], v[6:9]
	v_mfma_f32_16x16x32_bf16 v[14:17], v[118:121], v[180:183], v[14:17]
	v_mfma_f32_16x16x32_bf16 v[98:101], v[114:117], v[172:175], v[26:29]
	v_mfma_f32_16x16x32_bf16 v[66:69], v[114:117], v[2:5], v[30:33]
	v_mfma_f32_16x16x32_bf16 v[34:37], v[114:117], v[176:179], v[34:37]
	v_mfma_f32_16x16x32_bf16 v[10:13], v[114:117], v[180:183], v[138:141]
	v_mfma_f32_16x16x32_bf16 v[94:97], v[110:113], v[172:175], v[42:45]
	v_mfma_f32_16x16x32_bf16 v[46:49], v[110:113], v[2:5], v[46:49]
	v_mfma_f32_16x16x32_bf16 v[30:33], v[110:113], v[176:179], v[142:145]
	v_mfma_f32_16x16x32_bf16 v[6:9], v[110:113], v[180:183], v[146:149]
	v_mfma_f32_16x16x32_bf16 v[90:93], v[106:109], v[172:175], v[90:93]
	v_mfma_f32_16x16x32_bf16 v[42:45], v[106:109], v[2:5], v[150:153]
	v_mfma_f32_16x16x32_bf16 v[26:29], v[106:109], v[176:179], v[154:157]
	v_mfma_f32_16x16x32_bf16 v[2:5], v[106:109], v[180:183], v[158:161]
	s_and_b64 vcc, exec, s[8:9]
	s_cbranch_vccnz .LBB0_464
	v_add_co_u32_e32 v106, vcc, 0xa0000, v166
	s_nop 1
	v_addc_co_u32_e32 v107, vcc, 0, v167, vcc
	global_load_dwordx4 v[118:121], v[106:107], off
	global_load_dwordx4 v[114:117], v[106:107], off offset:1024
	global_load_dwordx4 v[110:113], v[106:107], off offset:2048
	s_nop 0
	global_load_dwordx4 v[106:109], v[106:107], off offset:3072
.LBB0_464:
	v_cndmask_b32_e64 v138, 0, 1, s[36:37]
	s_and_b64 vcc, exec, s[10:11]
	v_cmp_ne_u32_e64 s[6:7], 1, v138
	s_cbranch_vccnz .LBB0_468
	ds_read_b128 v[138:141], v162 offset:16512
	ds_read_b128 v[142:145], v162 offset:24960
	ds_read_b128 v[146:149], v162 offset:33408
	ds_read_b128 v[150:153], v162 offset:41856
	s_cmp_lg_u32 s75, 1
	s_cbranch_scc1 .Lw5_4_0
	s_waitcnt vmcnt(4)
	s_branch .Lw5_4_z

.Lw5_4_z:
	s_waitcnt lgkmcnt(3)
	v_mfma_f32_16x16x32_bf16 v[102:105], v[82:85], v[138:141], v[102:105]
	s_waitcnt lgkmcnt(2)
	v_mfma_f32_16x16x32_bf16 v[86:89], v[82:85], v[142:145], v[86:89]
	s_waitcnt lgkmcnt(1)
	v_mfma_f32_16x16x32_bf16 v[38:41], v[82:85], v[146:149], v[38:41]
	s_waitcnt lgkmcnt(0)
	v_mfma_f32_16x16x32_bf16 v[14:17], v[82:85], v[150:153], v[14:17]
	v_mfma_f32_16x16x32_bf16 v[98:101], v[74:77], v[138:141], v[98:101]
	v_mfma_f32_16x16x32_bf16 v[66:69], v[74:77], v[142:145], v[66:69]
	v_mfma_f32_16x16x32_bf16 v[34:37], v[74:77], v[146:149], v[34:37]
	v_mfma_f32_16x16x32_bf16 v[10:13], v[74:77], v[150:153], v[10:13]
	v_mfma_f32_16x16x32_bf16 v[94:97], v[78:81], v[138:141], v[94:97]
	v_mfma_f32_16x16x32_bf16 v[46:49], v[78:81], v[142:145], v[46:49]
	v_mfma_f32_16x16x32_bf16 v[30:33], v[78:81], v[146:149], v[30:33]
	v_mfma_f32_16x16x32_bf16 v[6:9], v[78:81], v[150:153], v[6:9]
	v_mfma_f32_16x16x32_bf16 v[90:93], v[70:73], v[138:141], v[90:93]
	v_mfma_f32_16x16x32_bf16 v[42:45], v[70:73], v[142:145], v[42:45]
	v_mfma_f32_16x16x32_bf16 v[26:29], v[70:73], v[146:149], v[26:29]
	v_mfma_f32_16x16x32_bf16 v[2:5], v[70:73], v[150:153], v[2:5]
	s_and_b64 vcc, exec, s[6:7]
	s_cbranch_vccnz .LBB0_467
	v_add_co_u32_e32 v70, vcc, 0xc0000, v166
	s_nop 1
	v_addc_co_u32_e32 v71, vcc, 0, v167, vcc
	global_load_dwordx4 v[82:85], v[70:71], off
	global_load_dwordx4 v[74:77], v[70:71], off offset:1024
	global_load_dwordx4 v[78:81], v[70:71], off offset:2048
	s_nop 0
	global_load_dwordx4 v[70:73], v[70:71], off offset:3072
.LBB0_467:
.LBB0_468:
	s_and_b64 vcc, exec, s[10:11]
	s_cbranch_vccnz .LBB0_472
	ds_read_b128 v[138:141], v162 offset:16576
	ds_read_b128 v[142:145], v162 offset:25024
	ds_read_b128 v[146:149], v162 offset:33472
	ds_read_b128 v[150:153], v162 offset:41920
	s_cmp_lg_u32 s75, 1
	s_cbranch_scc1 .Lw5_3_0
	s_waitcnt vmcnt(0)
	s_branch .Lw5_3_z
.Lw5_3_0:
	s_cmp_lg_u32 s75, 2
	s_cbranch_scc1 .Lw5_3_1
	s_waitcnt vmcnt(8)
	s_branch .Lw5_3_z

.Lw5_3_z:
	s_waitcnt lgkmcnt(3)
	v_mfma_f32_16x16x32_bf16 v[102:105], v[62:65], v[138:141], v[102:105]
	s_waitcnt lgkmcnt(2)
	v_mfma_f32_16x16x32_bf16 v[86:89], v[62:65], v[142:145], v[86:89]
	s_waitcnt lgkmcnt(1)
	v_mfma_f32_16x16x32_bf16 v[38:41], v[62:65], v[146:149], v[38:41]
	s_waitcnt lgkmcnt(0)
	v_mfma_f32_16x16x32_bf16 v[14:17], v[62:65], v[150:153], v[14:17]
	v_mfma_f32_16x16x32_bf16 v[98:101], v[58:61], v[138:141], v[98:101]
	v_mfma_f32_16x16x32_bf16 v[66:69], v[58:61], v[142:145], v[66:69]
	v_mfma_f32_16x16x32_bf16 v[34:37], v[58:61], v[146:149], v[34:37]
	v_mfma_f32_16x16x32_bf16 v[10:13], v[58:61], v[150:153], v[10:13]
	v_mfma_f32_16x16x32_bf16 v[94:97], v[54:57], v[138:141], v[94:97]
	v_mfma_f32_16x16x32_bf16 v[46:49], v[54:57], v[142:145], v[46:49]
	v_mfma_f32_16x16x32_bf16 v[30:33], v[54:57], v[146:149], v[30:33]
	v_mfma_f32_16x16x32_bf16 v[6:9], v[54:57], v[150:153], v[6:9]
	v_mfma_f32_16x16x32_bf16 v[90:93], v[50:53], v[138:141], v[90:93]
	v_mfma_f32_16x16x32_bf16 v[42:45], v[50:53], v[142:145], v[42:45]
	v_mfma_f32_16x16x32_bf16 v[26:29], v[50:53], v[146:149], v[26:29]
	v_mfma_f32_16x16x32_bf16 v[2:5], v[50:53], v[150:153], v[2:5]
	s_and_b64 vcc, exec, s[6:7]
	s_cbranch_vccnz .LBB0_471
	v_add_co_u32_e32 v50, vcc, 0xe0000, v166
	s_nop 1
	v_addc_co_u32_e32 v51, vcc, 0, v167, vcc
	global_load_dwordx4 v[62:65], v[50:51], off
	global_load_dwordx4 v[58:61], v[50:51], off offset:1024
	global_load_dwordx4 v[54:57], v[50:51], off offset:2048
	s_nop 0
	global_load_dwordx4 v[50:53], v[50:51], off offset:3072
.LBB0_471:
.LBB0_472:
	s_and_b64 vcc, exec, s[8:9]
	s_cbranch_vccnz .LBB0_482
	ds_read_b128 v[138:141], v162 offset:16640
	ds_read_b128 v[142:145], v162 offset:25088
	ds_read_b128 v[146:149], v162 offset:33536
	ds_read_b128 v[150:153], v162 offset:41984
	s_cmp_lg_u32 s75, 2
	s_cbranch_scc1 .Lw5_2_0
	s_waitcnt vmcnt(4)
	s_branch .Lw5_2_z

.Lw5_2_z:
	s_waitcnt lgkmcnt(3)
	v_mfma_f32_16x16x32_bf16 v[102:105], v[134:137], v[138:141], v[102:105]
	s_waitcnt lgkmcnt(2)
	v_mfma_f32_16x16x32_bf16 v[86:89], v[134:137], v[142:145], v[86:89]
	s_waitcnt lgkmcnt(1)
	v_mfma_f32_16x16x32_bf16 v[38:41], v[134:137], v[146:149], v[38:41]
	s_waitcnt lgkmcnt(0)
	v_mfma_f32_16x16x32_bf16 v[14:17], v[134:137], v[150:153], v[14:17]
	v_mfma_f32_16x16x32_bf16 v[98:101], v[130:133], v[138:141], v[98:101]
	v_mfma_f32_16x16x32_bf16 v[66:69], v[130:133], v[142:145], v[66:69]
	v_mfma_f32_16x16x32_bf16 v[34:37], v[130:133], v[146:149], v[34:37]
	v_mfma_f32_16x16x32_bf16 v[10:13], v[130:133], v[150:153], v[10:13]
	v_mfma_f32_16x16x32_bf16 v[94:97], v[126:129], v[138:141], v[94:97]
	v_mfma_f32_16x16x32_bf16 v[46:49], v[126:129], v[142:145], v[46:49]
	v_mfma_f32_16x16x32_bf16 v[30:33], v[126:129], v[146:149], v[30:33]
	v_mfma_f32_16x16x32_bf16 v[6:9], v[126:129], v[150:153], v[6:9]
	v_mfma_f32_16x16x32_bf16 v[90:93], v[122:125], v[138:141], v[90:93]
	v_mfma_f32_16x16x32_bf16 v[42:45], v[122:125], v[142:145], v[42:45]
	v_mfma_f32_16x16x32_bf16 v[26:29], v[122:125], v[146:149], v[26:29]
	v_mfma_f32_16x16x32_bf16 v[2:5], v[122:125], v[150:153], v[2:5]
	s_and_b64 vcc, exec, s[8:9]
	s_cbranch_vccz .LBB0_483

.LBB0_475:
	s_waitcnt vmcnt(4)
	ds_read_b128 v[106:109], v162 offset:16768
	ds_read_b128 v[110:113], v162 offset:25216
	ds_read_b128 v[114:117], v162 offset:33664
	ds_read_b128 v[118:121], v162 offset:42112
	s_waitcnt lgkmcnt(3)
	v_mfma_f32_16x16x32_bf16 v[102:105], v[82:85], v[106:109], v[102:105]
	s_waitcnt lgkmcnt(2)
	v_mfma_f32_16x16x32_bf16 v[86:89], v[82:85], v[110:113], v[86:89]
	s_waitcnt lgkmcnt(1)
	v_mfma_f32_16x16x32_bf16 v[38:41], v[82:85], v[114:117], v[38:41]
	s_waitcnt lgkmcnt(0)
	v_mfma_f32_16x16x32_bf16 v[14:17], v[82:85], v[118:121], v[14:17]
	v_mfma_f32_16x16x32_bf16 v[98:101], v[74:77], v[106:109], v[98:101]
	v_mfma_f32_16x16x32_bf16 v[66:69], v[74:77], v[110:113], v[66:69]
	v_mfma_f32_16x16x32_bf16 v[34:37], v[74:77], v[114:117], v[34:37]
	v_mfma_f32_16x16x32_bf16 v[10:13], v[74:77], v[118:121], v[10:13]
	v_mfma_f32_16x16x32_bf16 v[94:97], v[78:81], v[106:109], v[94:97]
	v_mfma_f32_16x16x32_bf16 v[46:49], v[78:81], v[110:113], v[46:49]
	v_mfma_f32_16x16x32_bf16 v[30:33], v[78:81], v[114:117], v[30:33]
	v_mfma_f32_16x16x32_bf16 v[6:9], v[78:81], v[118:121], v[6:9]
	v_mfma_f32_16x16x32_bf16 v[90:93], v[70:73], v[106:109], v[90:93]
	v_mfma_f32_16x16x32_bf16 v[42:45], v[70:73], v[110:113], v[42:45]
	v_mfma_f32_16x16x32_bf16 v[26:29], v[70:73], v[114:117], v[26:29]
	v_mfma_f32_16x16x32_bf16 v[2:5], v[70:73], v[118:121], v[2:5]
	s_and_b64 vcc, exec, s[6:7]
	s_cbranch_vccz .LBB0_485
	s_branch .LBB0_486

.LBB0_483:
	ds_read_b128 v[122:125], v162 offset:16704
	ds_read_b128 v[126:129], v162 offset:25152
	ds_read_b128 v[130:133], v162 offset:33600
	ds_read_b128 v[134:137], v162 offset:42048
	s_cmp_lg_u32 s75, 2
	s_cbranch_scc1 .Lw5_1_0
	s_waitcnt vmcnt(0) lgkmcnt(3)
	s_branch .Lw5_1_z
.Lw5_1_0:
	s_waitcnt vmcnt(8) lgkmcnt(3)
.Lw5_1_z:
	v_mfma_f32_16x16x32_bf16 v[102:105], v[118:121], v[122:125], v[102:105]
	s_waitcnt lgkmcnt(2)
	v_mfma_f32_16x16x32_bf16 v[86:89], v[118:121], v[126:129], v[86:89]
	s_waitcnt lgkmcnt(1)
	v_mfma_f32_16x16x32_bf16 v[38:41], v[118:121], v[130:133], v[38:41]
	s_waitcnt lgkmcnt(0)
	v_mfma_f32_16x16x32_bf16 v[14:17], v[118:121], v[134:137], v[14:17]
	v_mfma_f32_16x16x32_bf16 v[98:101], v[114:117], v[122:125], v[98:101]
	v_mfma_f32_16x16x32_bf16 v[66:69], v[114:117], v[126:129], v[66:69]
	v_mfma_f32_16x16x32_bf16 v[34:37], v[114:117], v[130:133], v[34:37]
	v_mfma_f32_16x16x32_bf16 v[10:13], v[114:117], v[134:137], v[10:13]
	v_mfma_f32_16x16x32_bf16 v[94:97], v[110:113], v[122:125], v[94:97]
	v_mfma_f32_16x16x32_bf16 v[46:49], v[110:113], v[126:129], v[46:49]
	v_mfma_f32_16x16x32_bf16 v[30:33], v[110:113], v[130:133], v[30:33]
	v_mfma_f32_16x16x32_bf16 v[6:9], v[110:113], v[134:137], v[6:9]
	v_mfma_f32_16x16x32_bf16 v[90:93], v[106:109], v[122:125], v[90:93]
	v_mfma_f32_16x16x32_bf16 v[42:45], v[106:109], v[126:129], v[42:45]
	v_mfma_f32_16x16x32_bf16 v[26:29], v[106:109], v[130:133], v[26:29]
	v_mfma_f32_16x16x32_bf16 v[2:5], v[106:109], v[134:137], v[2:5]
	s_and_b64 vcc, exec, s[6:7]
	s_cbranch_vccz .LBB0_475
